# attention compute block hand-scheduled: all 24 LDS reads up front into dedicated VGPRs, counted lgkmcnt, no mid-MFMA LDS stalls, scalar f32 ops; plus GEMM per-tile duplicate acc zeroing removed
# speedup vs baseline: 1.0158x; 1.0079x over previous
.LBB0_121:
	s_or_b64 exec, exec, s[0:1]
	s_lshl_b32 s0, s14, 11
	s_waitcnt vmcnt(0)
	v_add_u32_e32 v0, s0, v79
	v_ashrrev_i32_e32 v1, 31, v0
	v_readlane_b32 s4, v251, 6
	v_lshlrev_b64 v[0:1], 12, v[0:1]
	v_readlane_b32 s5, v251, 7
	s_lshl_b32 s26, s13, 1
	v_readlane_b32 s2, v251, 8
	v_lshl_add_u64 v[0:1], s[4:5], 0, v[0:1]
	v_lshl_add_u64 v[0:1], v[0:1], 0, s[26:27]
	v_readlane_b32 s3, v251, 9
	v_lshl_add_u64 v[70:71], v[0:1], 0, v[152:153]
	v_add_u32_e32 v2, s13, v79
	v_mov_b64_e32 v[0:1], s[2:3]
	v_mad_i64_i32 v[0:1], s[2:3], v2, s23, v[0:1]
	s_ashr_i32 s1, s0, 31
	v_lshl_add_u64 v[0:1], s[0:1], 1, v[0:1]
	v_lshl_add_u64 v[72:73], v[0:1], 0, v[152:153]
	global_load_dwordx4 v[0:3], v[70:71], off offset:2048
	global_load_dwordx4 v[4:7], v[72:73], off
	global_load_dwordx4 v[8:11], v[72:73], off offset:128
	s_mov_b32 s1, 0x40000
	v_add_co_u32_e32 v12, vcc, s1, v70
	s_add_i32 s2, s10, s0
	s_nop 0
	v_addc_co_u32_e32 v13, vcc, 0, v71, vcc
	global_load_dwordx4 v[12:15], v[12:13], off offset:2048
	v_or_b32_e32 v20, s2, v63
	v_ashrrev_i32_e32 v21, 31, v20
	v_add_co_u32_e32 v24, vcc, s25, v70
	v_lshlrev_b64 v[20:21], 12, v[20:21]
	s_nop 0
	v_addc_co_u32_e32 v25, vcc, 0, v71, vcc
	v_lshl_add_u64 v[20:21], s[4:5], 0, v[20:21]
	v_add_co_u32_e32 v26, vcc, s31, v70
	v_add_u32_e32 v96, 0x18c00, v92
	v_lshl_add_u64 v[20:21], v[20:21], 0, s[26:27]
	v_addc_co_u32_e32 v27, vcc, 0, v71, vcc
	v_add_u32_e32 v93, 0x12000, v92
	v_add_u32_e32 v94, 0x14400, v92
	v_add_u32_e32 v95, 0x16800, v92
	global_load_dwordx4 v[16:19], v[72:73], off offset:256
	v_lshl_add_u64 v[32:33], v[56:57], 1, v[20:21]
	global_load_dwordx4 v[20:23], v[72:73], off offset:384
	global_load_dwordx4 v[28:31], v[24:25], off offset:2048
	s_nop 0
	global_load_dwordx4 v[24:27], v[26:27], off offset:2048
	v_mov_b32_e32 v100, 0
	s_mov_b32 s1, 0
	s_or_b32 s0, s0, s8
	v_lshl_add_u64 v[74:75], v[58:59], 0, s[26:27]
	v_lshl_add_u64 v[76:77], v[60:61], 0, s[26:27]
	v_mov_b32_e32 v101, 0xf149f2ca
	s_mov_b32 s15, 4
	s_mov_b32 s5, 8
	s_mov_b32 s3, -3
	v_mov_b32_e32 v97, 0
	v_mov_b32_e32 v98, 8
	v_mov_b32_e32 v99, 0
	s_mov_b32 s14, 0
	s_mov_b32 s13, s9
	s_mov_b32 s4, 0
	s_mov_b32 s16, 4
	v_mov_b32_e32 v34, v100
	v_mov_b32_e32 v35, v100
	v_mov_b32_e32 v36, v100
	v_mov_b32_e32 v37, v100
	v_mov_b32_e32 v38, v100
	v_mov_b32_e32 v39, v100
	v_mov_b32_e32 v40, v100
	v_mov_b32_e32 v41, v100
	v_mov_b32_e32 v42, v100
	v_mov_b32_e32 v43, v100
	v_mov_b32_e32 v44, v100
	v_mov_b32_e32 v45, v100
	v_mov_b32_e32 v46, v100
	v_mov_b32_e32 v47, v100
	s_waitcnt vmcnt(0)
	ds_write_b128 v96, v[8:11]
	ds_write_b128 v94, v[4:7]
	ds_write_b128 v93, v[0:3]
	s_waitcnt vmcnt(4)
	ds_write_b128 v95, v[12:15]
	s_waitcnt lgkmcnt(0)
	s_barrier
	global_load_dwordx4 v[0:3], v[32:33], off
	global_load_dwordx4 v[4:7], v[32:33], off offset:64
	v_mov_b32_e32 v8, v153
	v_mov_b32_e32 v9, v153
	v_mov_b32_e32 v10, v153
	v_mov_b32_e32 v11, v153
	v_mov_b32_e32 v12, v153
	v_mov_b32_e32 v13, v153
	v_mov_b32_e32 v14, v153
	v_mov_b32_e32 v15, v153
	v_mov_b32_e32 v32, 0
	v_mov_b32_e32 v33, v100
	v_add_u32_e32 v210, v82, v81
	v_add_u32_e32 v211, v83, v80
	s_branch .LBB0_123

.LBB0_152:
	v_mad_u32_u24 v103, v102, s34, v67
	v_subrev_u32_e32 v120, s13, v99
	v_lshl_add_u32 v137, v102, 6, v78
	ds_read_b128 v[166:169], v103 offset:3072
	ds_read_b128 v[174:177], v103 offset:5376
	ds_read_b128 v[170:173], v103 offset:3136
	ds_read_b128 v[178:181], v103 offset:5440
	v_add3_u32 v120, v120, v102, 7
	ds_read_b128 v[182:185], v210 offset:0
	ds_read_b128 v[190:193], v210 offset:576
	ds_read_b128 v[186:189], v210 offset:64
	ds_read_b128 v[194:197], v210 offset:640
	v_mul_u32_u24_e32 v120, 0xc0, v120
	v_lshl_add_u32 v121, v84, 2, v120
	v_lshl_add_u32 v122, v86, 2, v120
	v_lshl_add_u32 v123, v88, 2, v120
	v_lshl_add_u32 v124, v90, 2, v120
	v_lshl_add_u32 v125, v85, 2, v120
	v_lshl_add_u32 v126, v87, 2, v120
	v_lshl_add_u32 v127, v89, 2, v120
	v_lshl_add_u32 v120, v91, 2, v120
	ds_read_b32 v112, v121
	ds_read_b32 v113, v122
	ds_read_b32 v114, v123
	ds_read_b32 v115, v124
	ds_read_b32 v116, v125
	ds_read_b32 v117, v126
	ds_read_b32 v118, v127
	ds_read_b32 v119, v120
	s_waitcnt lgkmcnt(12)
	v_mfma_f32_16x16x32_bf16 v[104:107], v[166:169], v[8:11], 0
	ds_read_b128 v[198:201], v137 offset:39936
	ds_read_b128 v[202:205], v137 offset:48384
	v_mfma_f32_16x16x32_bf16 v[108:111], v[174:177], v[8:11], 0
	ds_read_b128 v[206:209], v137 offset:56832
	ds_read_b128 v[232:235], v137 offset:65280
	v_mfma_f32_16x16x32_bf16 v[104:107], v[170:173], v[12:15], v[104:107]
	ds_read_b128 v[236:239], v211 offset:0
	ds_read_b128 v[240:243], v211 offset:2304
	v_mfma_f32_16x16x32_bf16 v[108:111], v[178:181], v[12:15], v[108:111]
	ds_read_b128 v[244:247], v211 offset:4608
	ds_read_b128 v[228:231], v211 offset:6912
	s_waitcnt lgkmcnt(8)
	v_mfma_f32_16x16x32_bf16 v[112:115], v[182:185], v[8:11], v[112:115]
	v_mfma_f32_16x16x32_bf16 v[116:119], v[190:193], v[8:11], v[116:119]
	v_mfma_f32_16x16x32_bf16 v[112:115], v[186:189], v[12:15], v[112:115]
	v_mfma_f32_16x16x32_bf16 v[116:119], v[194:197], v[12:15], v[116:119]
	v_max3_f32 v121, v104, v105, v106
	v_max3_f32 v122, v108, v109, v110
	v_max_f32_e32 v121, v121, v107
	v_max3_f32 v121, v121, v122, v111
	s_nop 3
	v_max3_f32 v122, v112, v113, v114
	v_max3_f32 v123, v116, v117, v118
	v_max3_f32 v121, v121, v115, v119
	v_max3_f32 v121, v121, v122, v123
	v_mov_b32_e32 v122, v121
	s_nop 1
	v_permlane16_swap_b32_e32 v121, v122
	v_max_f32_e32 v121, v121, v122
	v_mov_b32_e32 v122, v121
	s_nop 1
	v_permlane32_swap_b32_e32 v121, v122
	v_max3_f32 v157, v101, v121, v122
	v_sub_f32_e32 v164, v101, v157
	v_sub_f32_e32 v104, v104, v157
	v_sub_f32_e32 v105, v105, v157
	v_sub_f32_e32 v106, v106, v157
	v_sub_f32_e32 v107, v107, v157
	v_sub_f32_e32 v108, v108, v157
	v_sub_f32_e32 v109, v109, v157
	v_sub_f32_e32 v110, v110, v157
	v_sub_f32_e32 v111, v111, v157
	v_sub_f32_e32 v112, v112, v157
	v_sub_f32_e32 v113, v113, v157
	v_sub_f32_e32 v114, v114, v157
	v_sub_f32_e32 v115, v115, v157
	v_sub_f32_e32 v116, v116, v157
	v_sub_f32_e32 v117, v117, v157
	v_sub_f32_e32 v118, v118, v157
	v_sub_f32_e32 v119, v119, v157
	v_exp_f32_e32 v164, v164
	v_exp_f32_e32 v104, v104
	v_exp_f32_e32 v105, v105
	v_mul_f32_e32 v32, v32, v164
	v_exp_f32_e32 v106, v106
	v_mul_f32_e32 v33, v33, v164
	v_exp_f32_e32 v107, v107
	v_mul_f32_e32 v34, v34, v164
	v_exp_f32_e32 v108, v108
	v_mul_f32_e32 v35, v35, v164
	v_exp_f32_e32 v109, v109
	v_mul_f32_e32 v36, v36, v164
	v_exp_f32_e32 v110, v110
	v_mul_f32_e32 v37, v37, v164
	v_exp_f32_e32 v111, v111
	v_mul_f32_e32 v38, v38, v164
	v_exp_f32_e32 v112, v112
	v_mul_f32_e32 v39, v39, v164
	v_exp_f32_e32 v113, v113
	v_mul_f32_e32 v40, v40, v164
	v_exp_f32_e32 v114, v114
	v_mul_f32_e32 v41, v41, v164
	v_exp_f32_e32 v115, v115
	v_mul_f32_e32 v42, v42, v164
	v_exp_f32_e32 v116, v116
	v_mul_f32_e32 v43, v43, v164
	v_exp_f32_e32 v117, v117
	v_mul_f32_e32 v44, v44, v164
	v_exp_f32_e32 v118, v118
	v_mul_f32_e32 v45, v45, v164
	v_exp_f32_e32 v119, v119
	v_mul_f32_e32 v46, v46, v164
	v_mul_f32_e32 v47, v47, v164
	v_cvt_pk_bf16_f32 v124, v104, v105
	v_cvt_pk_bf16_f32 v125, v106, v107
	v_cvt_pk_bf16_f32 v126, v108, v109
	v_cvt_pk_bf16_f32 v127, v110, v111
	v_cvt_pk_bf16_f32 v128, v112, v113
	v_cvt_pk_bf16_f32 v129, v114, v115
	v_cvt_pk_bf16_f32 v130, v116, v117
	v_cvt_pk_bf16_f32 v131, v118, v119
	s_waitcnt lgkmcnt(4)
	v_mfma_f32_16x16x32_bf16 v[32:35], v[198:201], v[124:127], v[32:35]
	v_add_f32_e32 v132, v104, v108
	v_add_f32_e32 v133, v105, v109
	v_mfma_f32_16x16x32_bf16 v[36:39], v[202:205], v[124:127], v[36:39]
	v_add_f32_e32 v134, v106, v110
	v_add_f32_e32 v135, v107, v111
	v_mfma_f32_16x16x32_bf16 v[40:43], v[206:209], v[124:127], v[40:43]
	v_add_f32_e32 v140, v112, v116
	v_add_f32_e32 v141, v113, v117
	v_mfma_f32_16x16x32_bf16 v[44:47], v[232:235], v[124:127], v[44:47]
	v_add_f32_e32 v142, v114, v118
	v_add_f32_e32 v143, v115, v119
	s_waitcnt lgkmcnt(0)
	v_mfma_f32_16x16x32_bf16 v[32:35], v[236:239], v[128:131], v[32:35]
	v_add_f32_e32 v132, v132, v140
	v_add_f32_e32 v133, v133, v141
	v_mfma_f32_16x16x32_bf16 v[36:39], v[240:243], v[128:131], v[36:39]
	v_add_f32_e32 v134, v134, v142
	v_add_f32_e32 v135, v135, v143
	v_mfma_f32_16x16x32_bf16 v[40:43], v[244:247], v[128:131], v[40:43]
	v_add_f32_e32 v132, v132, v133
	v_add_f32_e32 v134, v134, v135
	v_mfma_f32_16x16x32_bf16 v[44:47], v[228:231], v[128:131], v[44:47]
	v_add_f32_e32 v132, v132, v134
	v_fmac_f32_e32 v132, v100, v164
	v_mov_b32_e32 v100, v132
	v_mov_b32_e32 v101, v157
	s_add_i32 s16, s5, -1
	s_cmp_lg_u32 s14, s16
	s_cbranch_scc1 .LBB0_131

.LBB0_154:
	v_mad_u32_u24 v103, v102, s34, v67
	v_subrev_u32_e32 v120, s13, v99
	v_lshl_add_u32 v137, v102, 6, v78
	ds_read_b128 v[166:169], v103 offset:3072
	ds_read_b128 v[174:177], v103 offset:5376
	ds_read_b128 v[170:173], v103 offset:3136
	ds_read_b128 v[178:181], v103 offset:5440
	v_add3_u32 v120, v120, v102, 7
	ds_read_b128 v[182:185], v210 offset:18432
	ds_read_b128 v[190:193], v210 offset:19008
	ds_read_b128 v[186:189], v210 offset:18496
	ds_read_b128 v[194:197], v210 offset:19072
	v_mul_u32_u24_e32 v120, 0xc0, v120
	v_lshl_add_u32 v121, v84, 2, v120
	v_lshl_add_u32 v122, v86, 2, v120
	v_lshl_add_u32 v123, v88, 2, v120
	v_lshl_add_u32 v124, v90, 2, v120
	v_lshl_add_u32 v125, v85, 2, v120
	v_lshl_add_u32 v126, v87, 2, v120
	v_lshl_add_u32 v127, v89, 2, v120
	v_lshl_add_u32 v120, v91, 2, v120
	ds_read_b32 v112, v121
	ds_read_b32 v113, v122
	ds_read_b32 v114, v123
	ds_read_b32 v115, v124
	ds_read_b32 v116, v125
	ds_read_b32 v117, v126
	ds_read_b32 v118, v127
	ds_read_b32 v119, v120
	s_waitcnt lgkmcnt(12)
	v_mfma_f32_16x16x32_bf16 v[104:107], v[166:169], v[8:11], 0
	ds_read_b128 v[198:201], v137 offset:39936
	ds_read_b128 v[202:205], v137 offset:48384
	v_mfma_f32_16x16x32_bf16 v[108:111], v[174:177], v[8:11], 0
	ds_read_b128 v[206:209], v137 offset:56832
	ds_read_b128 v[232:235], v137 offset:65280
	v_mfma_f32_16x16x32_bf16 v[104:107], v[170:173], v[12:15], v[104:107]
	ds_read_b128 v[236:239], v211 offset:18432
	ds_read_b128 v[240:243], v211 offset:20736
	v_mfma_f32_16x16x32_bf16 v[108:111], v[178:181], v[12:15], v[108:111]
	ds_read_b128 v[244:247], v211 offset:23040
	ds_read_b128 v[228:231], v211 offset:25344
	s_waitcnt lgkmcnt(8)
	v_mfma_f32_16x16x32_bf16 v[112:115], v[182:185], v[8:11], v[112:115]
	v_mfma_f32_16x16x32_bf16 v[116:119], v[190:193], v[8:11], v[116:119]
	v_mfma_f32_16x16x32_bf16 v[112:115], v[186:189], v[12:15], v[112:115]
	v_mfma_f32_16x16x32_bf16 v[116:119], v[194:197], v[12:15], v[116:119]
	v_max3_f32 v121, v104, v105, v106
	v_max3_f32 v122, v108, v109, v110
	v_max_f32_e32 v121, v121, v107
	v_max3_f32 v121, v121, v122, v111
	s_nop 3
	v_max3_f32 v122, v112, v113, v114
	v_max3_f32 v123, v116, v117, v118
	v_max3_f32 v121, v121, v115, v119
	v_max3_f32 v121, v121, v122, v123
	v_mov_b32_e32 v122, v121
	s_nop 1
	v_permlane16_swap_b32_e32 v121, v122
	v_max_f32_e32 v121, v121, v122
	v_mov_b32_e32 v122, v121
	s_nop 1
	v_permlane32_swap_b32_e32 v121, v122
	v_max3_f32 v157, v101, v121, v122
	v_sub_f32_e32 v164, v101, v157
	v_sub_f32_e32 v104, v104, v157
	v_sub_f32_e32 v105, v105, v157
	v_sub_f32_e32 v106, v106, v157
	v_sub_f32_e32 v107, v107, v157
	v_sub_f32_e32 v108, v108, v157
	v_sub_f32_e32 v109, v109, v157
	v_sub_f32_e32 v110, v110, v157
	v_sub_f32_e32 v111, v111, v157
	v_sub_f32_e32 v112, v112, v157
	v_sub_f32_e32 v113, v113, v157
	v_sub_f32_e32 v114, v114, v157
	v_sub_f32_e32 v115, v115, v157
	v_sub_f32_e32 v116, v116, v157
	v_sub_f32_e32 v117, v117, v157
	v_sub_f32_e32 v118, v118, v157
	v_sub_f32_e32 v119, v119, v157
	v_exp_f32_e32 v164, v164
	v_exp_f32_e32 v104, v104
	v_exp_f32_e32 v105, v105
	v_mul_f32_e32 v32, v32, v164
	v_exp_f32_e32 v106, v106
	v_mul_f32_e32 v33, v33, v164
	v_exp_f32_e32 v107, v107
	v_mul_f32_e32 v34, v34, v164
	v_exp_f32_e32 v108, v108
	v_mul_f32_e32 v35, v35, v164
	v_exp_f32_e32 v109, v109
	v_mul_f32_e32 v36, v36, v164
	v_exp_f32_e32 v110, v110
	v_mul_f32_e32 v37, v37, v164
	v_exp_f32_e32 v111, v111
	v_mul_f32_e32 v38, v38, v164
	v_exp_f32_e32 v112, v112
	v_mul_f32_e32 v39, v39, v164
	v_exp_f32_e32 v113, v113
	v_mul_f32_e32 v40, v40, v164
	v_exp_f32_e32 v114, v114
	v_mul_f32_e32 v41, v41, v164
	v_exp_f32_e32 v115, v115
	v_mul_f32_e32 v42, v42, v164
	v_exp_f32_e32 v116, v116
	v_mul_f32_e32 v43, v43, v164
	v_exp_f32_e32 v117, v117
	v_mul_f32_e32 v44, v44, v164
	v_exp_f32_e32 v118, v118
	v_mul_f32_e32 v45, v45, v164
	v_exp_f32_e32 v119, v119
	v_mul_f32_e32 v46, v46, v164
	v_mul_f32_e32 v47, v47, v164
	v_cvt_pk_bf16_f32 v124, v104, v105
	v_cvt_pk_bf16_f32 v125, v106, v107
	v_cvt_pk_bf16_f32 v126, v108, v109
	v_cvt_pk_bf16_f32 v127, v110, v111
	v_cvt_pk_bf16_f32 v128, v112, v113
	v_cvt_pk_bf16_f32 v129, v114, v115
	v_cvt_pk_bf16_f32 v130, v116, v117
	v_cvt_pk_bf16_f32 v131, v118, v119
	s_waitcnt lgkmcnt(4)
	v_mfma_f32_16x16x32_bf16 v[32:35], v[198:201], v[124:127], v[32:35]
	v_add_f32_e32 v132, v104, v108
	v_add_f32_e32 v133, v105, v109
	v_mfma_f32_16x16x32_bf16 v[36:39], v[202:205], v[124:127], v[36:39]
	v_add_f32_e32 v134, v106, v110
	v_add_f32_e32 v135, v107, v111
	v_mfma_f32_16x16x32_bf16 v[40:43], v[206:209], v[124:127], v[40:43]
	v_add_f32_e32 v140, v112, v116
	v_add_f32_e32 v141, v113, v117
	v_mfma_f32_16x16x32_bf16 v[44:47], v[232:235], v[124:127], v[44:47]
	v_add_f32_e32 v142, v114, v118
	v_add_f32_e32 v143, v115, v119
	s_waitcnt lgkmcnt(0)
	v_mfma_f32_16x16x32_bf16 v[32:35], v[236:239], v[128:131], v[32:35]
	v_add_f32_e32 v132, v132, v140
	v_add_f32_e32 v133, v133, v141
	v_mfma_f32_16x16x32_bf16 v[36:39], v[240:243], v[128:131], v[36:39]
	v_add_f32_e32 v134, v134, v142
	v_add_f32_e32 v135, v135, v143
	v_mfma_f32_16x16x32_bf16 v[40:43], v[244:247], v[128:131], v[40:43]
	v_add_f32_e32 v132, v132, v133
	v_add_f32_e32 v134, v134, v135
	v_mfma_f32_16x16x32_bf16 v[44:47], v[228:231], v[128:131], v[44:47]
	v_add_f32_e32 v132, v132, v134
	v_fmac_f32_e32 v132, v100, v164
	v_mov_b32_e32 v100, v132
	v_mov_b32_e32 v101, v157
	s_add_i32 s15, s5, -1
	s_cmp_lg_u32 s14, s15
	s_cbranch_scc1 .LBB0_141

.LBB0_156:
	v_mad_u32_u24 v103, v102, s34, v67
	v_subrev_u32_e32 v120, s13, v99
	v_lshl_add_u32 v137, v102, 6, v78
	ds_read_b128 v[166:169], v103 offset:3072
	ds_read_b128 v[174:177], v103 offset:5376
	ds_read_b128 v[170:173], v103 offset:3136
	ds_read_b128 v[178:181], v103 offset:5440
	v_add3_u32 v120, v120, v102, 7
	ds_read_b128 v[182:185], v210 offset:36864
	ds_read_b128 v[190:193], v210 offset:37440
	ds_read_b128 v[186:189], v210 offset:36928
	ds_read_b128 v[194:197], v210 offset:37504
	v_mul_u32_u24_e32 v120, 0xc0, v120
	v_lshl_add_u32 v121, v84, 2, v120
	v_lshl_add_u32 v122, v86, 2, v120
	v_lshl_add_u32 v123, v88, 2, v120
	v_lshl_add_u32 v124, v90, 2, v120
	v_lshl_add_u32 v125, v85, 2, v120
	v_lshl_add_u32 v126, v87, 2, v120
	v_lshl_add_u32 v127, v89, 2, v120
	v_lshl_add_u32 v120, v91, 2, v120
	ds_read_b32 v112, v121
	ds_read_b32 v113, v122
	ds_read_b32 v114, v123
	ds_read_b32 v115, v124
	ds_read_b32 v116, v125
	ds_read_b32 v117, v126
	ds_read_b32 v118, v127
	ds_read_b32 v119, v120
	s_waitcnt lgkmcnt(12)
	v_mfma_f32_16x16x32_bf16 v[104:107], v[166:169], v[8:11], 0
	ds_read_b128 v[198:201], v137 offset:39936
	ds_read_b128 v[202:205], v137 offset:48384
	v_mfma_f32_16x16x32_bf16 v[108:111], v[174:177], v[8:11], 0
	ds_read_b128 v[206:209], v137 offset:56832
	ds_read_b128 v[232:235], v137 offset:65280
	v_mfma_f32_16x16x32_bf16 v[104:107], v[170:173], v[12:15], v[104:107]
	ds_read_b128 v[236:239], v211 offset:36864
	ds_read_b128 v[240:243], v211 offset:39168
	v_mfma_f32_16x16x32_bf16 v[108:111], v[178:181], v[12:15], v[108:111]
	ds_read_b128 v[244:247], v211 offset:41472
	ds_read_b128 v[228:231], v211 offset:43776
	s_waitcnt lgkmcnt(8)
	v_mfma_f32_16x16x32_bf16 v[112:115], v[182:185], v[8:11], v[112:115]
	v_mfma_f32_16x16x32_bf16 v[116:119], v[190:193], v[8:11], v[116:119]
	v_mfma_f32_16x16x32_bf16 v[112:115], v[186:189], v[12:15], v[112:115]
	v_mfma_f32_16x16x32_bf16 v[116:119], v[194:197], v[12:15], v[116:119]
	v_max3_f32 v121, v104, v105, v106
	v_max3_f32 v122, v108, v109, v110
	v_max_f32_e32 v121, v121, v107
	v_max3_f32 v121, v121, v122, v111
	s_nop 3
	v_max3_f32 v122, v112, v113, v114
	v_max3_f32 v123, v116, v117, v118
	v_max3_f32 v121, v121, v115, v119
	v_max3_f32 v121, v121, v122, v123
	v_mov_b32_e32 v122, v121
	s_nop 1
	v_permlane16_swap_b32_e32 v121, v122
	v_max_f32_e32 v121, v121, v122
	v_mov_b32_e32 v122, v121
	s_nop 1
	v_permlane32_swap_b32_e32 v121, v122
	v_max3_f32 v157, v101, v121, v122
	v_sub_f32_e32 v164, v101, v157
	v_sub_f32_e32 v104, v104, v157
	v_sub_f32_e32 v105, v105, v157
	v_sub_f32_e32 v106, v106, v157
	v_sub_f32_e32 v107, v107, v157
	v_sub_f32_e32 v108, v108, v157
	v_sub_f32_e32 v109, v109, v157
	v_sub_f32_e32 v110, v110, v157
	v_sub_f32_e32 v111, v111, v157
	v_sub_f32_e32 v112, v112, v157
	v_sub_f32_e32 v113, v113, v157
	v_sub_f32_e32 v114, v114, v157
	v_sub_f32_e32 v115, v115, v157
	v_sub_f32_e32 v116, v116, v157
	v_sub_f32_e32 v117, v117, v157
	v_sub_f32_e32 v118, v118, v157
	v_sub_f32_e32 v119, v119, v157
	v_exp_f32_e32 v164, v164
	v_exp_f32_e32 v104, v104
	v_exp_f32_e32 v105, v105
	v_mul_f32_e32 v32, v32, v164
	v_exp_f32_e32 v106, v106
	v_mul_f32_e32 v33, v33, v164
	v_exp_f32_e32 v107, v107
	v_mul_f32_e32 v34, v34, v164
	v_exp_f32_e32 v108, v108
	v_mul_f32_e32 v35, v35, v164
	v_exp_f32_e32 v109, v109
	v_mul_f32_e32 v36, v36, v164
	v_exp_f32_e32 v110, v110
	v_mul_f32_e32 v37, v37, v164
	v_exp_f32_e32 v111, v111
	v_mul_f32_e32 v38, v38, v164
	v_exp_f32_e32 v112, v112
	v_mul_f32_e32 v39, v39, v164
	v_exp_f32_e32 v113, v113
	v_mul_f32_e32 v40, v40, v164
	v_exp_f32_e32 v114, v114
	v_mul_f32_e32 v41, v41, v164
	v_exp_f32_e32 v115, v115
	v_mul_f32_e32 v42, v42, v164
	v_exp_f32_e32 v116, v116
	v_mul_f32_e32 v43, v43, v164
	v_exp_f32_e32 v117, v117
	v_mul_f32_e32 v44, v44, v164
	v_exp_f32_e32 v118, v118
	v_mul_f32_e32 v45, v45, v164
	v_exp_f32_e32 v119, v119
	v_mul_f32_e32 v46, v46, v164
	v_mul_f32_e32 v47, v47, v164
	v_cvt_pk_bf16_f32 v124, v104, v105
	v_cvt_pk_bf16_f32 v125, v106, v107
	v_cvt_pk_bf16_f32 v126, v108, v109
	v_cvt_pk_bf16_f32 v127, v110, v111
	v_cvt_pk_bf16_f32 v128, v112, v113
	v_cvt_pk_bf16_f32 v129, v114, v115
	v_cvt_pk_bf16_f32 v130, v116, v117
	v_cvt_pk_bf16_f32 v131, v118, v119
	s_waitcnt lgkmcnt(4)
	v_mfma_f32_16x16x32_bf16 v[32:35], v[198:201], v[124:127], v[32:35]
	v_add_f32_e32 v132, v104, v108
	v_add_f32_e32 v133, v105, v109
	v_mfma_f32_16x16x32_bf16 v[36:39], v[202:205], v[124:127], v[36:39]
	v_add_f32_e32 v134, v106, v110
	v_add_f32_e32 v135, v107, v111
	v_mfma_f32_16x16x32_bf16 v[40:43], v[206:209], v[124:127], v[40:43]
	v_add_f32_e32 v140, v112, v116
	v_add_f32_e32 v141, v113, v117
	v_mfma_f32_16x16x32_bf16 v[44:47], v[232:235], v[124:127], v[44:47]
	v_add_f32_e32 v142, v114, v118
	v_add_f32_e32 v143, v115, v119
	s_waitcnt lgkmcnt(0)
	v_mfma_f32_16x16x32_bf16 v[32:35], v[236:239], v[128:131], v[32:35]
	v_add_f32_e32 v132, v132, v140
	v_add_f32_e32 v133, v133, v141
	v_mfma_f32_16x16x32_bf16 v[36:39], v[240:243], v[128:131], v[36:39]
	v_add_f32_e32 v134, v134, v142
	v_add_f32_e32 v135, v135, v143
	v_mfma_f32_16x16x32_bf16 v[40:43], v[244:247], v[128:131], v[40:43]
	v_add_f32_e32 v132, v132, v133
	v_add_f32_e32 v134, v134, v135
	v_mfma_f32_16x16x32_bf16 v[44:47], v[228:231], v[128:131], v[44:47]
	v_add_f32_e32 v132, v132, v134
	v_fmac_f32_e32 v132, v100, v164
	v_mov_b32_e32 v100, v132
	v_mov_b32_e32 v101, v157
	s_add_i32 s17, s5, -1
	s_cmp_lg_u32 s14, s17
	s_cbranch_scc1 .LBB0_151

.LBB0_246:
	v_mov_b32_e32 v19, 0
	s_andn2_b64 vcc, exec, s[18:19]
	v_mov_b32_e32 v18, v19
	v_mov_b32_e32 v17, v19
	v_mov_b32_e32 v16, v19
	v_mov_b32_e32 v31, v19
	v_mov_b32_e32 v30, v19
	v_mov_b32_e32 v29, v19
	v_mov_b32_e32 v28, v19
	v_mov_b32_e32 v15, v19
	v_mov_b32_e32 v14, v19
	v_mov_b32_e32 v13, v19
	v_mov_b32_e32 v12, v19
	v_mov_b32_e32 v11, v19
	v_mov_b32_e32 v10, v19
	v_mov_b32_e32 v9, v19
	v_mov_b32_e32 v8, v19
	v_mov_b32_e32 v127, v19
	v_mov_b32_e32 v126, v19
	v_mov_b32_e32 v125, v19
	v_mov_b32_e32 v124, v19
	v_mov_b32_e32 v123, v19
	v_mov_b32_e32 v122, v19
	v_mov_b32_e32 v121, v19
	v_mov_b32_e32 v120, v19
	v_mov_b32_e32 v111, v19
	v_mov_b32_e32 v110, v19
	v_mov_b32_e32 v109, v19
	v_mov_b32_e32 v108, v19
	v_mov_b32_e32 v107, v19
	v_mov_b32_e32 v106, v19
	v_mov_b32_e32 v105, v19
	v_mov_b32_e32 v104, v19
	v_mov_b32_e32 v27, v19
	v_mov_b32_e32 v26, v19
	v_mov_b32_e32 v25, v19
	v_mov_b32_e32 v24, v19
	v_mov_b32_e32 v23, v19
	v_mov_b32_e32 v22, v19
	v_mov_b32_e32 v21, v19
	v_mov_b32_e32 v20, v19
	v_mov_b32_e32 v7, v19
	v_mov_b32_e32 v6, v19
	v_mov_b32_e32 v5, v19
	v_mov_b32_e32 v4, v19
	v_mov_b32_e32 v3, v19
	v_mov_b32_e32 v2, v19
	v_mov_b32_e32 v1, v19
	v_mov_b32_e32 v0, v19
	v_mov_b32_e32 v119, v19
	v_mov_b32_e32 v118, v19
	v_mov_b32_e32 v117, v19
	v_mov_b32_e32 v116, v19
	v_mov_b32_e32 v115, v19
	v_mov_b32_e32 v114, v19
	v_mov_b32_e32 v113, v19
	v_mov_b32_e32 v112, v19
	v_mov_b32_e32 v103, v19
	v_mov_b32_e32 v102, v19
	v_mov_b32_e32 v101, v19
	v_mov_b32_e32 v100, v19
	v_mov_b32_e32 v99, v19
	v_mov_b32_e32 v98, v19
	v_mov_b32_e32 v97, v19
	v_mov_b32_e32 v96, v19
	v_mov_b32_e32 v95, v19
	v_mov_b32_e32 v94, v19
	v_mov_b32_e32 v93, v19
	v_mov_b32_e32 v92, v19
	v_mov_b32_e32 v91, v19
	v_mov_b32_e32 v90, v19
	v_mov_b32_e32 v89, v19
	v_mov_b32_e32 v88, v19
	v_mov_b32_e32 v79, v19
	v_mov_b32_e32 v78, v19
	v_mov_b32_e32 v77, v19
	v_mov_b32_e32 v76, v19
	v_mov_b32_e32 v75, v19
	v_mov_b32_e32 v74, v19
	v_mov_b32_e32 v73, v19
	v_mov_b32_e32 v72, v19
	v_mov_b32_e32 v63, v19
	v_mov_b32_e32 v62, v19
	v_mov_b32_e32 v61, v19
	v_mov_b32_e32 v60, v19
	v_mov_b32_e32 v59, v19
	v_mov_b32_e32 v58, v19
	v_mov_b32_e32 v57, v19
	v_mov_b32_e32 v56, v19
	v_mov_b32_e32 v47, v19
	v_mov_b32_e32 v46, v19
	v_mov_b32_e32 v45, v19
	v_mov_b32_e32 v44, v19
	v_mov_b32_e32 v43, v19
	v_mov_b32_e32 v42, v19
	v_mov_b32_e32 v41, v19
	v_mov_b32_e32 v40, v19
	v_mov_b32_e32 v87, v19
	v_mov_b32_e32 v86, v19
	v_mov_b32_e32 v85, v19
	v_mov_b32_e32 v84, v19
	v_mov_b32_e32 v83, v19
	v_mov_b32_e32 v82, v19
	v_mov_b32_e32 v81, v19
	v_mov_b32_e32 v80, v19
	v_mov_b32_e32 v71, v19
	v_mov_b32_e32 v70, v19
	v_mov_b32_e32 v69, v19
	v_mov_b32_e32 v68, v19
	v_mov_b32_e32 v67, v19
	v_mov_b32_e32 v66, v19
	v_mov_b32_e32 v65, v19
	v_mov_b32_e32 v64, v19
	v_mov_b32_e32 v55, v19
	v_mov_b32_e32 v54, v19
	v_mov_b32_e32 v53, v19
	v_mov_b32_e32 v52, v19
	v_mov_b32_e32 v51, v19
	v_mov_b32_e32 v50, v19
	v_mov_b32_e32 v49, v19
	v_mov_b32_e32 v48, v19
	v_mov_b32_e32 v39, v19
	v_mov_b32_e32 v38, v19
	v_mov_b32_e32 v37, v19
	v_mov_b32_e32 v36, v19
	v_mov_b32_e32 v35, v19
	v_mov_b32_e32 v34, v19
	v_mov_b32_e32 v33, v19
	v_mov_b32_e32 v32, v19
	s_cbranch_vccnz .LBB0_249
	s_add_u32 s44, s44, 0x80
	s_addc_u32 s45, s45, 0
	s_add_u32 s23, s46, 0x100
	s_addc_u32 s48, s47, 0
	s_mov_b32 s46, 0
